# counted waits: attention A tile pieces issued K,K,V,V and end-of-step wait relaxed to vmcnt(6) so the next tile's V pieces stay in flight (only K is needed right after the barrier)
# baseline (speedup 1.0000x reference)
; #define ATT_PKN(P, BASE, OUT) do { u32x4 w = {cvtpk(P[BASE + 0], P[BASE + 1]), cvtpk(P[BASE + 2], P[BASE + 3]), cvtpk(P[BASE + 4], P[BASE + 5]), cvtpk(P[BASE + 6], P[BASE + 7])}; OUT = *reinterpret_cast<bf16x8*>(&w); } while (0)
; __device__ __forceinline__ void finishSM(f32x16& p0, f32x16& p1, float alpha, float& l_reg, bf16x8& pa0, bf16x8& pa1, bf16x8& pa2, bf16x8& pa3) {
; #pragma unroll
;   for (int r = 0; r < 16; ++r) p1[r] = __builtin_amdgcn_exp2f(p1[r]);
;   float ps = 0;
; #pragma unroll
;   for (int r = 0; r < 16; ++r) ps += p0[r];
; #pragma unroll
;   for (int r = 0; r < 16; ++r) ps += p1[r];
;   { auto rr = __builtin_amdgcn_permlane32_swap(__float_as_uint(ps), __float_as_uint(ps), false, false);
;     ps = __uint_as_float(rr[0]) + __uint_as_float(rr[1]); }
;   l_reg = l_reg * alpha + ps;
;     ...
;   ATT_PKN(p0, 0, pa0); ATT_PKN(p0, 8, pa1); ATT_PKN(p1, 0, pa2); ATT_PKN(p1, 8, pa3);
;     ...
; }
; __device__ __forceinline__ void qkt(f32x16& p0, f32x16& p1, const bf16* Ks, const bf16x8* qr, int r32, int hi, int mp, const f32x16& negm) {
; #pragma unroll
;   for (int d0 = 0; d0 < 4; ++d0) { int cb = ((mp * 4 + d0) * 16 + hi * 8) * 2;
;     bf16x8 b0 = *reinterpret_cast<const bf16x8*>((const char*)Ks + KSWZ(r32, cb));
;     bf16x8 b1 = *reinterpret_cast<const bf16x8*>((const char*)Ks + KSWZ(32 + r32, cb));
;     if (d0 == 0) { p0 = __builtin_amdgcn_mfma_f32_32x32x16_bf16(b0, qr[0], negm, 0, 0, 0); p1 = __builtin_amdgcn_mfma_f32_32x32x16_bf16(b1, qr[0], negm, 0, 0, 0); }
;     else { p0 = __builtin_amdgcn_mfma_f32_32x32x16_bf16(b0, qr[d0], p0, 0, 0, 0); p1 = __builtin_amdgcn_mfma_f32_32x32x16_bf16(b1, qr[d0], p1, 0, 0, 0); } }
; }
; __device__ __forceinline__ void unit(const bf16* Qb, const bf16* __restrict__ Kh, const bf16* __restrict__ Vh, bf16* Ob, float lam, float post, const float* __restrict__ gsub, char* lds) {
;     ...
;   f32x16 pA0, pA1, pB0, pB1; float alA, alB; bf16x8 pa0, pa1, pa2, pa3; constexpr int NT = 4096 / KVBLK;
;   DMA_TILE(0, 0); DMA_TILE(1, 32768); DMA_TILE(2, 65536);
;   asm volatile("s_waitcnt vmcnt(0)" ::: "memory"); __syncthreads();
;   qkt(pA0, pA1, (const bf16*)(lds + 16384), qr, r32, hi, mp, negm); partialSM<true>(pA0, pA1, m_reg, negm, alA);
;   int sk = 32768, sv = 0, sw = 98304;
.Lprio_skip:
.LBB0_197:
	s_add_i32 s10, s39, 0
	s_add_i32 s13, s21, s56
	s_add_u32 s58, s50, s36
	s_addc_u32 s59, s51, s37
	s_add_u32 s60, s50, 0x4030000
	s_addc_u32 s61, s51, 0
	s_add_u32 s62, s60, 0x80
	s_addc_u32 s63, s61, 0
	v_add_u32_e32 v112, s10, v202
	ds_read_b128 v[236:239], v112 offset:24576
	ds_read_b128 v[112:115], v112 offset:16384
	v_add_u32_e32 v208, s10, v201
	ds_read_b128 v[68:71], v208 offset:24576
	ds_read_b128 v[72:75], v208 offset:16384
	v_add_u32_e32 v208, s10, v199
	v_exp_f32_e32 v210, v96
	v_add_f32_e32 v96, v174, v172
	s_waitcnt lgkmcnt(2)
	v_mfma_f32_32x32x16_bf16 v[128:143], v[112:115], v[158:161], v[80:95]
	v_add_f32_e32 v96, v175, v96
	v_add_f32_e32 v96, v211, v96
	v_mfma_f32_32x32x16_bf16 v[112:127], v[236:239], v[158:161], v[80:95]
	ds_read_b128 v[236:239], v208 offset:24576
	ds_read_b128 v[240:243], v208 offset:16384
	s_add_i32 m0, s13, 0x4000
	s_nop 0
	global_load_lds_dwordx4 v168, s[58:59]
	v_add_u32_e32 v208, s10, v183
	v_add_f32_e32 v96, v212, v96
	v_add_f32_e32 v96, v215, v96
	v_add_f32_e32 v96, v216, v96
	v_add_f32_e32 v96, v233, v96
	v_add_f32_e32 v96, v173, v96
	s_waitcnt lgkmcnt(2)
	v_mfma_f32_32x32x16_bf16 v[112:127], v[68:71], v[154:157], v[112:127]
	v_add_f32_e32 v96, v176, v96
	v_add_f32_e32 v96, v177, v96
	v_add_f32_e32 v96, v213, v96
	v_add_f32_e32 v96, v214, v96
	v_exp_f32_e32 v235, v97
	v_add_f32_e32 v96, v217, v96
	v_add_f32_e32 v96, v232, v96
	v_mfma_f32_32x32x16_bf16 v[128:143], v[72:75], v[154:157], v[128:143]
	ds_read_b128 v[68:71], v208 offset:24576
	ds_read_b128 v[72:75], v208 offset:16384
	s_add_i32 m0, s13, 0x4400
	s_nop 0
	global_load_lds_dwordx4 v170, s[58:59]
	v_add_f32_e32 v96, v234, v96
	v_add_f32_e32 v96, v210, v96
	v_add_f32_e32 v96, v235, v96
	v_exp_f32_e32 v244, v106
	v_exp_f32_e32 v245, v107
	s_waitcnt lgkmcnt(2)
	v_mfma_f32_32x32x16_bf16 v[112:127], v[236:239], v[150:153], v[112:127]
	v_exp_f32_e32 v246, v108
	v_exp_f32_e32 v247, v109
	v_exp_f32_e32 v248, v110
	v_exp_f32_e32 v111, v111
	v_cvt_pk_bf16_f32 v97, v175, v211
	v_cvt_pk_bf16_f32 v109, v244, v245
	v_cvt_pk_bf16_f32 v110, v246, v247
	v_mfma_f32_32x32x16_bf16 v[128:143], v[240:243], v[150:153], v[128:143]
	s_mov_b32 m0, s13
	s_nop 0
	global_load_lds_dwordx4 v188, s[60:61]
	s_waitcnt lgkmcnt(0)
	v_mfma_f32_32x32x16_bf16 v[112:127], v[68:71], v[146:149], v[112:127]
	v_exp_f32_e32 v236, v98
	v_exp_f32_e32 v237, v99
	v_exp_f32_e32 v238, v100
	v_exp_f32_e32 v239, v101
	v_add_f32_e32 v96, v236, v96
	v_add_f32_e32 v96, v237, v96
	v_add_f32_e32 v96, v238, v96
	v_mfma_f32_32x32x16_bf16 v[128:143], v[72:75], v[146:149], v[128:143]
	s_add_i32 m0, s13, 0x400
	s_nop 0
	global_load_lds_dwordx4 v188, s[62:63]
	v_exp_f32_e32 v240, v102
	v_exp_f32_e32 v241, v103
	v_exp_f32_e32 v242, v104
	v_exp_f32_e32 v243, v105
	v_add_f32_e32 v96, v239, v96
	v_add_f32_e32 v96, v240, v96
	v_add_f32_e32 v96, v241, v96
	v_add_f32_e32 v96, v242, v96
	v_add_f32_e32 v96, v243, v96
	v_add_f32_e32 v96, v244, v96
	v_add_f32_e32 v96, v245, v96
	v_add_f32_e32 v96, v246, v96
	v_add_f32_e32 v96, v247, v96
	v_add_f32_e32 v96, v248, v96
	v_add_f32_e32 v208, v111, v96
	v_mov_b32_e32 v209, v208
	s_nop 1
	v_permlane32_swap_b32_e32 v208, v209
	v_cvt_pk_bf16_f32 v96, v172, v174
	v_cvt_pk_bf16_f32 v98, v212, v215
	v_cvt_pk_bf16_f32 v99, v216, v233
	v_cvt_pk_bf16_f32 v100, v173, v176
	v_cvt_pk_bf16_f32 v101, v177, v213
	v_cvt_pk_bf16_f32 v102, v214, v217
	v_cvt_pk_bf16_f32 v103, v232, v234
	v_cvt_pk_bf16_f32 v104, v210, v235
	v_cvt_pk_bf16_f32 v105, v236, v237
	v_cvt_pk_bf16_f32 v106, v238, v239
	v_cvt_pk_bf16_f32 v107, v240, v241
	v_cvt_pk_bf16_f32 v108, v242, v243
	v_cvt_pk_bf16_f32 v111, v248, v111
	v_add_u32_e32 v240, s48, v205
	ds_read_b64_tr_b16 v[210:211], v240 offset:0
	ds_read_b64_tr_b16 v[212:213], v240 offset:0x800
	ds_read_b64_tr_b16 v[214:215], v240 offset:0x1000
	ds_read_b64_tr_b16 v[216:217], v240 offset:0x1800
	ds_read_b64_tr_b16 v[232:233], v240 offset:0x2000
	ds_read_b64_tr_b16 v[234:235], v240 offset:0x2800
	ds_read_b64_tr_b16 v[236:237], v240 offset:0x3000
	ds_read_b64_tr_b16 v[238:239], v240 offset:0x3800
	s_waitcnt lgkmcnt(0)
; #define SBAR() __builtin_amdgcn_sched_barrier(0)
; template <int OFF> __device__ __forceinline__ s16x4 tr_read(int vb) { s16x4 r; asm volatile("ds_read_b64_tr_b16 %0, %1 offset:%2" : "=&v"(r) : "v"(vb), "i"(OFF) : "memory"); return r; }
; template <bool FIRST> __device__ __forceinline__ void partialSM(f32x16& p0, f32x16& p1, float& m_reg, f32x16& negm, float& alpha) {
;   float pmax = p0[0];
; #pragma unroll
;   for (int r = 1; r < 16; ++r) pmax = fmaxf(pmax, p0[r]);
; #pragma unroll
;   for (int r = 0; r < 16; ++r) pmax = fmaxf(pmax, p1[r]);
;   { auto rr = __builtin_amdgcn_permlane32_swap(__float_as_uint(pmax), __float_as_uint(pmax), false, false);
;     pmax = fmaxf(__uint_as_float(rr[0]), __uint_as_float(rr[1])); }
;   alpha = 1.f;
;   if (FIRST || __builtin_expect(__any(pmax > THR), 0)) { const float dl = FIRST ? pmax : fmaxf(pmax, 0.f); m_reg += dl; if (!FIRST) alpha = __builtin_amdgcn_exp2f(-dl);
; template <int D0> __device__ __forceinline__ void pv_one(f32x16& od, int vb, bf16x8 pa0, bf16x8 pa1, bf16x8 pa2, bf16x8 pa3) {
;   const s16x4 l0 = tr_read<v_rd_off(D0, 0, 0)>(vb), h0 = tr_read<v_rd_off(D0, 0, 1)>(vb), l1 = tr_read<v_rd_off(D0, 1, 0)>(vb), h1 = tr_read<v_rd_off(D0, 1, 1)>(vb);
;   const s16x4 l2 = tr_read<v_rd_off(D0, 2, 0)>(vb), h2 = tr_read<v_rd_off(D0, 2, 1)>(vb), l3 = tr_read<v_rd_off(D0, 3, 0)>(vb), h3 = tr_read<v_rd_off(D0, 3, 1)>(vb);
;   asm volatile("s_waitcnt lgkmcnt(0)" ::: "memory"); SBAR();
;   od = __builtin_amdgcn_mfma_f32_32x32x16_bf16(pa0, ATT_PK(l0, h0), od, 0, 0, 0);
;   od = __builtin_amdgcn_mfma_f32_32x32x16_bf16(pa1, ATT_PK(l1, h1), od, 0, 0, 0);
;   od = __builtin_amdgcn_mfma_f32_32x32x16_bf16(pa2, ATT_PK(l2, h2), od, 0, 0, 0);
;   od = __builtin_amdgcn_mfma_f32_32x32x16_bf16(pa3, ATT_PK(l3, h3), od, 0, 0, 0);
; }
; __device__ __forceinline__ void pv_d0(f32x16* o, int vb, bf16x8 pa0, bf16x8 pa1, bf16x8 pa2, bf16x8 pa3) {
;   pv_one<0>(o[0], vb, pa0, pa1, pa2, pa3); pv_one<1>(o[1], vb, pa0, pa1, pa2, pa3); pv_one<2>(o[2], vb, pa0, pa1, pa2, pa3); pv_one<3>(o[3], vb, pa0, pa1, pa2, pa3);
	s_nop 0
	v_mfma_f32_32x32x16_bf16 v[0:15], v[96:99], v[210:213], v[0:15]
	ds_read_b64_tr_b16 v[210:211], v240 offset:0x200
	ds_read_b64_tr_b16 v[212:213], v240 offset:0xa00
	v_mfma_f32_32x32x16_bf16 v[0:15], v[100:103], v[214:217], v[0:15]
	ds_read_b64_tr_b16 v[214:215], v240 offset:0x1200
	ds_read_b64_tr_b16 v[216:217], v240 offset:0x1a00
	v_mfma_f32_32x32x16_bf16 v[0:15], v[104:107], v[232:235], v[0:15]
	ds_read_b64_tr_b16 v[232:233], v240 offset:0x2200
	ds_read_b64_tr_b16 v[234:235], v240 offset:0x2a00
	v_mfma_f32_32x32x16_bf16 v[0:15], v[108:111], v[236:239], v[0:15]
	ds_read_b64_tr_b16 v[236:237], v240 offset:0x3200
	ds_read_b64_tr_b16 v[238:239], v240 offset:0x3a00
	s_waitcnt lgkmcnt(0)
	v_mfma_f32_32x32x16_bf16 v[48:63], v[96:99], v[210:213], v[48:63]
	ds_read_b64_tr_b16 v[210:211], v240 offset:0x400
	ds_read_b64_tr_b16 v[212:213], v240 offset:0xc00
	v_mfma_f32_32x32x16_bf16 v[48:63], v[100:103], v[214:217], v[48:63]
	ds_read_b64_tr_b16 v[214:215], v240 offset:0x1400
	ds_read_b64_tr_b16 v[216:217], v240 offset:0x1c00
	v_mfma_f32_32x32x16_bf16 v[48:63], v[104:107], v[232:235], v[48:63]
	ds_read_b64_tr_b16 v[232:233], v240 offset:0x2400
	ds_read_b64_tr_b16 v[234:235], v240 offset:0x2c00
	v_mfma_f32_32x32x16_bf16 v[48:63], v[108:111], v[236:239], v[48:63]
	ds_read_b64_tr_b16 v[236:237], v240 offset:0x3400
	ds_read_b64_tr_b16 v[238:239], v240 offset:0x3c00
	s_waitcnt lgkmcnt(0)
	v_mfma_f32_32x32x16_bf16 v[32:47], v[96:99], v[210:213], v[32:47]
	ds_read_b64_tr_b16 v[210:211], v240 offset:0x600
	ds_read_b64_tr_b16 v[212:213], v240 offset:0xe00
	v_mfma_f32_32x32x16_bf16 v[32:47], v[100:103], v[214:217], v[32:47]
	ds_read_b64_tr_b16 v[214:215], v240 offset:0x1600
	ds_read_b64_tr_b16 v[216:217], v240 offset:0x1e00
	v_mfma_f32_32x32x16_bf16 v[32:47], v[104:107], v[232:235], v[32:47]
	ds_read_b64_tr_b16 v[232:233], v240 offset:0x2600
	ds_read_b64_tr_b16 v[234:235], v240 offset:0x2e00
	v_mfma_f32_32x32x16_bf16 v[32:47], v[108:111], v[236:239], v[32:47]
	ds_read_b64_tr_b16 v[236:237], v240 offset:0x3600
	ds_read_b64_tr_b16 v[238:239], v240 offset:0x3e00
	s_waitcnt lgkmcnt(0)
	v_mfma_f32_32x32x16_bf16 v[16:31], v[96:99], v[210:213], v[16:31]
	v_max_f32_e32 v96, v129, v129
	v_max_f32_e32 v97, v128, v128
	v_max_f32_e32 v96, v97, v96
	v_max3_f32 v96, v96, v130, v131
	v_max3_f32 v96, v96, v132, v133
	v_max3_f32 v96, v96, v134, v135
	v_max3_f32 v96, v96, v136, v137
	v_mfma_f32_32x32x16_bf16 v[16:31], v[100:103], v[214:217], v[16:31]
	v_max3_f32 v96, v96, v138, v139
	v_max3_f32 v96, v96, v140, v141
	v_max3_f32 v96, v96, v142, v143
	v_max3_f32 v96, v96, v112, v113
	v_max3_f32 v96, v96, v114, v115
	v_max3_f32 v96, v96, v116, v117
	v_max3_f32 v96, v96, v118, v119
	v_mfma_f32_32x32x16_bf16 v[16:31], v[104:107], v[232:235], v[16:31]
	v_max3_f32 v96, v96, v120, v121
	v_max3_f32 v96, v96, v122, v123
	v_max3_f32 v96, v96, v124, v125
	v_max3_f32 v96, v96, v126, v127
	v_mov_b32_e32 v97, v96
	s_nop 1
	v_permlane32_swap_b32_e32 v96, v97
	v_mfma_f32_32x32x16_bf16 v[16:31], v[108:111], v[236:239], v[16:31]
	v_max_f32_e32 v96, v96, v97
	v_cmp_lt_f32_e32 vcc, s19, v96
	s_cbranch_vccnz .LBB0_215
	v_mov_b32_e32 v210, 1.0
	s_branch .LBB0_202

; #define ATT_PKN(P, BASE, OUT) do { u32x4 w = {cvtpk(P[BASE + 0], P[BASE + 1]), cvtpk(P[BASE + 2], P[BASE + 3]), cvtpk(P[BASE + 4], P[BASE + 5]), cvtpk(P[BASE + 6], P[BASE + 7])}; OUT = *reinterpret_cast<bf16x8*>(&w); } while (0)
; template <bool FIRST> __device__ __forceinline__ void partialSM(f32x16& p0, f32x16& p1, float& m_reg, f32x16& negm, float& alpha) {
;     ...
;   for (int r = 0; r < 16; ++r) p0[r] = __builtin_amdgcn_exp2f(p0[r]);
; }
; __device__ __forceinline__ void finishSM(f32x16& p0, f32x16& p1, float alpha, float& l_reg, bf16x8& pa0, bf16x8& pa1, bf16x8& pa2, bf16x8& pa3) {
; #pragma unroll
;   for (int r = 0; r < 16; ++r) p1[r] = __builtin_amdgcn_exp2f(p1[r]);
;   float ps = 0;
; #pragma unroll
;   for (int r = 0; r < 16; ++r) ps += p0[r];
; #pragma unroll
;   for (int r = 0; r < 16; ++r) ps += p1[r];
;   { auto rr = __builtin_amdgcn_permlane32_swap(__float_as_uint(ps), __float_as_uint(ps), false, false);
;     ps = __uint_as_float(rr[0]) + __uint_as_float(rr[1]); }
;   l_reg = l_reg * alpha + ps;
;     ...
;   ATT_PKN(p0, 0, pa0); ATT_PKN(p0, 8, pa1); ATT_PKN(p1, 0, pa2); ATT_PKN(p1, 8, pa3);
;     ...
; }
; __device__ __forceinline__ void qkt(f32x16& p0, f32x16& p1, const bf16* Ks, const bf16x8* qr, int r32, int hi, int mp, const f32x16& negm) {
; #pragma unroll
;   for (int d0 = 0; d0 < 4; ++d0) { int cb = ((mp * 4 + d0) * 16 + hi * 8) * 2;
;     bf16x8 b0 = *reinterpret_cast<const bf16x8*>((const char*)Ks + KSWZ(r32, cb));
;     bf16x8 b1 = *reinterpret_cast<const bf16x8*>((const char*)Ks + KSWZ(32 + r32, cb));
;     if (d0 == 0) { p0 = __builtin_amdgcn_mfma_f32_32x32x16_bf16(b0, qr[0], negm, 0, 0, 0); p1 = __builtin_amdgcn_mfma_f32_32x32x16_bf16(b1, qr[0], negm, 0, 0, 0); }
;     else { p0 = __builtin_amdgcn_mfma_f32_32x32x16_bf16(b0, qr[d0], p0, 0, 0, 0); p1 = __builtin_amdgcn_mfma_f32_32x32x16_bf16(b1, qr[d0], p1, 0, 0, 0); } }
; }
.LBB0_202:
	v_exp_f32_e32 v211, v128
	v_exp_f32_e32 v213, v129
	v_exp_f32_e32 v214, v130
	v_exp_f32_e32 v217, v131
	v_exp_f32_e32 v232, v132
	v_exp_f32_e32 v235, v133
	v_exp_f32_e32 v236, v134
	v_exp_f32_e32 v239, v135
	v_exp_f32_e32 v212, v136
	v_exp_f32_e32 v215, v137
	v_exp_f32_e32 v216, v138
	v_exp_f32_e32 v233, v139
	v_exp_f32_e32 v234, v140
	v_exp_f32_e32 v237, v141
	v_exp_f32_e32 v238, v142
	v_exp_f32_e32 v240, v143
	s_waitcnt vmcnt(6) lgkmcnt(0)
	s_barrier
	s_add_i32 s10, s39, 0x8000
	s_and_b32 s48, s10, 0x1ffff
	s_add_i32 s10, s48, 0
	v_add_u32_e32 v96, s10, v202
	ds_read_b128 v[242:245], v96 offset:24576
	ds_read_b128 v[96:99], v96 offset:16384
	v_add_u32_e32 v241, s10, v201
	v_exp_f32_e32 v112, v112
	v_exp_f32_e32 v115, v115
	v_exp_f32_e32 v116, v116
	s_waitcnt lgkmcnt(0)
	v_mfma_f32_32x32x16_bf16 v[128:143], v[96:99], v[158:161], v[80:95]
	v_exp_f32_e32 v117, v117
	v_exp_f32_e32 v118, v118
	v_mfma_f32_32x32x16_bf16 v[96:111], v[242:245], v[158:161], v[80:95]
	ds_read_b128 v[242:245], v241 offset:24576
	ds_read_b128 v[246:249], v241 offset:16384
	v_add_u32_e32 v241, s10, v199
	ds_read_b128 v[68:71], v241 offset:24576
	ds_read_b128 v[72:75], v241 offset:16384
	v_add_u32_e32 v241, s10, v183
	s_waitcnt lgkmcnt(2)
	v_mfma_f32_32x32x16_bf16 v[128:143], v[246:249], v[154:157], v[128:143]
	v_mfma_f32_32x32x16_bf16 v[96:111], v[242:245], v[154:157], v[96:111]
	ds_read_b128 v[242:245], v241 offset:24576
	ds_read_b128 v[246:249], v241 offset:16384
	s_waitcnt lgkmcnt(2)
	v_mfma_f32_32x32x16_bf16 v[128:143], v[72:75], v[150:153], v[128:143]
	v_mfma_f32_32x32x16_bf16 v[96:111], v[68:71], v[150:153], v[96:111]
	v_exp_f32_e32 v241, v113
	v_add_f32_e32 v113, v213, v211
	v_add_f32_e32 v113, v214, v113
	v_add_f32_e32 v113, v217, v113
	v_add_f32_e32 v113, v232, v113
	v_add_f32_e32 v113, v235, v113
	v_add_f32_e32 v113, v236, v113
	v_add_f32_e32 v113, v239, v113
	v_add_f32_e32 v113, v212, v113
	v_add_f32_e32 v113, v215, v113
	v_add_f32_e32 v113, v216, v113
	v_add_f32_e32 v113, v233, v113
	v_add_f32_e32 v113, v234, v113
	v_add_f32_e32 v113, v237, v113
	s_waitcnt lgkmcnt(0)
	v_mfma_f32_32x32x16_bf16 v[96:111], v[242:245], v[146:149], v[96:111]
	v_exp_f32_e32 v242, v114
	v_add_f32_e32 v113, v238, v113
	v_add_f32_e32 v113, v240, v113
	v_add_f32_e32 v113, v112, v113
	v_add_f32_e32 v113, v241, v113
	v_add_f32_e32 v113, v242, v113
	v_exp_f32_e32 v243, v119
	v_add_f32_e32 v113, v115, v113
	v_exp_f32_e32 v119, v120
	v_add_f32_e32 v113, v116, v113
	v_exp_f32_e32 v120, v121
	v_add_f32_e32 v113, v117, v113
	v_exp_f32_e32 v121, v122
	v_add_f32_e32 v113, v118, v113
	v_exp_f32_e32 v122, v123
	v_add_f32_e32 v113, v243, v113
	v_exp_f32_e32 v123, v124
	v_add_f32_e32 v113, v119, v113
	v_exp_f32_e32 v124, v125
	v_add_f32_e32 v113, v120, v113
	v_mfma_f32_32x32x16_bf16 v[128:143], v[246:249], v[146:149], v[128:143]
	v_exp_f32_e32 v125, v126
	v_add_f32_e32 v113, v121, v113
	v_exp_f32_e32 v126, v127
	v_add_f32_e32 v113, v122, v113
	v_add_f32_e32 v113, v123, v113
	v_add_f32_e32 v113, v124, v113
	v_add_f32_e32 v113, v125, v113
	v_add_f32_e32 v113, v126, v113
	v_mov_b32_e32 v114, v113
	s_nop 1
	v_permlane32_swap_b32_e32 v113, v114
	v_cvt_pk_bf16_f32 v250, v211, v213
	v_cvt_pk_bf16_f32 v251, v214, v217
	v_cvt_pk_bf16_f32 v252, v232, v235
	v_cvt_pk_bf16_f32 v253, v236, v239
	v_cvt_pk_bf16_f32 v212, v212, v215
	v_cvt_pk_bf16_f32 v213, v216, v233
	v_cvt_pk_bf16_f32 v214, v234, v237
	v_cvt_pk_bf16_f32 v215, v238, v240
	v_cvt_pk_bf16_f32 v232, v112, v241
	v_cvt_pk_bf16_f32 v233, v242, v115
	v_cvt_pk_bf16_f32 v234, v116, v117
	v_cvt_pk_bf16_f32 v235, v118, v243
	v_cvt_pk_bf16_f32 v116, v119, v120
	v_cvt_pk_bf16_f32 v117, v121, v122
	v_cvt_pk_bf16_f32 v118, v123, v124
	v_cvt_pk_bf16_f32 v119, v125, v126
	v_add_u32_e32 v112, s39, v205
	ds_read_b64_tr_b16 v[120:121], v112 offset:0
	ds_read_b64_tr_b16 v[122:123], v112 offset:0x800
	ds_read_b64_tr_b16 v[124:125], v112 offset:0x1000
	ds_read_b64_tr_b16 v[126:127], v112 offset:0x1800
	ds_read_b64_tr_b16 v[236:237], v112 offset:0x2000
	ds_read_b64_tr_b16 v[238:239], v112 offset:0x2800
	ds_read_b64_tr_b16 v[240:241], v112 offset:0x3000
	ds_read_b64_tr_b16 v[242:243], v112 offset:0x3800
	s_cmp_gt_u32 s44, 60
	s_cselect_b64 s[52:53], -1, 0
	s_and_b64 vcc, exec, s[52:53]
	s_cbranch_vccnz .LBB0_204
	s_add_i32 s10, s56, 0x8000
	s_and_b32 s10, s10, 0x1ffff
	s_add_i32 s12, s21, s10
	s_add_u32 s98, s50, s68
	s_addc_u32 s99, s51, s69
	s_add_u32 s100, s50, 0x4040000
	s_addc_u32 s101, s51, 0
	s_add_i32 m0, s12, 0x4000
	s_add_u32 s10, s100, 0x80
	s_addc_u32 s11, s101, 0
	global_load_lds_dwordx4 v168, s[98:99]
	s_add_i32 m0, s12, 0x4400
	s_nop 0
	global_load_lds_dwordx4 v170, s[98:99]
	s_mov_b32 m0, s12
	s_nop 0
	global_load_lds_dwordx4 v188, s[100:101]
	s_add_i32 m0, s12, 0x400
	s_nop 0
	global_load_lds_dwordx4 v188, s[10:11]

.LBB0_211:
	s_andn2_b64 vcc, exec, s[54:55]
	s_cbranch_vccnz .LBB0_213
	s_waitcnt vmcnt(6) lgkmcnt(0)
